# P1 K-loop: the compiler-inserted s_waitcnt vmcnt(0) at the loop top removed (the counted vmcnt(8) protocol already retires every tile before its first read)
# baseline (speedup 1.0000x reference)
.LBB0_120:
	ds_read_b128 v[130:133], v245
	ds_read_b128 v[134:137], v245 offset:1024
	ds_read_b128 v[138:141], v245 offset:2048
	ds_read_b128 v[142:145], v245 offset:3072
	ds_read_b128 v[146:149], v246
	ds_read_b128 v[150:153], v246 offset:1024
	ds_read_b128 v[154:157], v246 offset:2048
	ds_read_b128 v[158:161], v246 offset:3072
	s_add_u32 s16, s6, 0xfffc0080
	s_addc_u32 s17, s7, -1
	s_cmp_eq_u32 s40, 12
	s_cselect_b32 s79, s1, s17
	s_cselect_b32 s78, s2, s16
	s_cselect_b32 s17, s3, s37
	s_cselect_b32 s16, s9, s35
	s_add_i32 m0, s71, 0xc000
	ds_read_b128 v[162:165], v247
	ds_read_b128 v[166:169], v247 offset:1024
	ds_read_b128 v[170:173], v247 offset:2048
	ds_read_b128 v[174:177], v247 offset:3072
	ds_read_b128 v[178:181], v247 offset:4096
	ds_read_b128 v[182:185], v247 offset:5120
	ds_read_b128 v[186:189], v247 offset:6144
	ds_read_b128 v[190:193], v247 offset:7168
	global_load_lds_dwordx4 v226, s[6:7]
	s_add_i32 m0, s71, 0xe000
	s_nop 0
	global_load_lds_dwordx4 v228, s[6:7]
	s_waitcnt vmcnt(8)
	s_waitcnt lgkmcnt(0)
	s_barrier
	s_setprio 1
	s_waitcnt lgkmcnt(0)
	v_mfma_f32_16x16x32_bf16 v[126:129], v[130:133], v[162:165], v[126:129]
	v_mfma_f32_16x16x32_bf16 v[122:125], v[138:141], v[162:165], v[122:125]
	v_mfma_f32_16x16x32_bf16 v[110:113], v[130:133], v[170:173], v[110:113]
	v_mfma_f32_16x16x32_bf16 v[106:109], v[138:141], v[170:173], v[106:109]
	v_mfma_f32_16x16x32_bf16 v[94:97], v[130:133], v[178:181], v[94:97]
	v_mfma_f32_16x16x32_bf16 v[90:93], v[138:141], v[178:181], v[90:93]
	v_mfma_f32_16x16x32_bf16 v[78:81], v[130:133], v[186:189], v[78:81]
	v_mfma_f32_16x16x32_bf16 v[74:77], v[138:141], v[186:189], v[74:77]
	v_mfma_f32_16x16x32_bf16 v[126:129], v[134:137], v[166:169], v[126:129]
	v_mfma_f32_16x16x32_bf16 v[122:125], v[142:145], v[166:169], v[122:125]
	v_mfma_f32_16x16x32_bf16 v[110:113], v[134:137], v[174:177], v[110:113]
	v_mfma_f32_16x16x32_bf16 v[106:109], v[142:145], v[174:177], v[106:109]
	v_mfma_f32_16x16x32_bf16 v[94:97], v[134:137], v[182:185], v[94:97]
	v_mfma_f32_16x16x32_bf16 v[90:93], v[142:145], v[182:185], v[90:93]
	v_mfma_f32_16x16x32_bf16 v[78:81], v[134:137], v[190:193], v[78:81]
	v_mfma_f32_16x16x32_bf16 v[74:77], v[142:145], v[190:193], v[74:77]
	s_setprio 0
	s_setprio 1
	v_mfma_f32_16x16x32_bf16 v[118:121], v[146:149], v[162:165], v[118:121]
	v_mfma_f32_16x16x32_bf16 v[114:117], v[154:157], v[162:165], v[114:117]
	v_mfma_f32_16x16x32_bf16 v[102:105], v[146:149], v[170:173], v[102:105]
	v_mfma_f32_16x16x32_bf16 v[98:101], v[154:157], v[170:173], v[98:101]
	v_mfma_f32_16x16x32_bf16 v[86:89], v[146:149], v[178:181], v[86:89]
	v_mfma_f32_16x16x32_bf16 v[82:85], v[154:157], v[178:181], v[82:85]
	v_mfma_f32_16x16x32_bf16 v[70:73], v[146:149], v[186:189], v[70:73]
	v_mfma_f32_16x16x32_bf16 v[66:69], v[154:157], v[186:189], v[66:69]
	v_mfma_f32_16x16x32_bf16 v[118:121], v[150:153], v[166:169], v[118:121]
	v_mfma_f32_16x16x32_bf16 v[114:117], v[158:161], v[166:169], v[114:117]
	v_mfma_f32_16x16x32_bf16 v[102:105], v[150:153], v[174:177], v[102:105]
	v_mfma_f32_16x16x32_bf16 v[98:101], v[158:161], v[174:177], v[98:101]
	v_mfma_f32_16x16x32_bf16 v[86:89], v[150:153], v[182:185], v[86:89]
	v_mfma_f32_16x16x32_bf16 v[82:85], v[158:161], v[182:185], v[82:85]
	v_mfma_f32_16x16x32_bf16 v[70:73], v[150:153], v[190:193], v[70:73]
	v_mfma_f32_16x16x32_bf16 v[66:69], v[158:161], v[190:193], v[66:69]
	s_setprio 0
	s_barrier
	s_add_i32 s41, s12, s39
	s_mov_b32 m0, s41
	ds_read_b128 v[162:165], v247 offset:16384
	ds_read_b128 v[166:169], v247 offset:17408
	ds_read_b128 v[170:173], v247 offset:18432
	ds_read_b128 v[174:177], v247 offset:19456
	ds_read_b128 v[178:181], v247 offset:20480
	ds_read_b128 v[182:185], v247 offset:21504
	ds_read_b128 v[186:189], v247 offset:22528
	ds_read_b128 v[190:193], v247 offset:23552
	global_load_lds_dwordx4 v212, s[16:17]
	s_add_i32 m0, s41, 0x2000
	s_add_u32 s42, s16, 0x40000
	s_addc_u32 s43, s17, 0
	s_add_i32 s41, s13, s39
	global_load_lds_dwordx4 v216, s[16:17]
	s_mov_b32 m0, s41
	s_nop 0
	global_load_lds_dwordx4 v212, s[42:43]
	s_add_i32 m0, s41, 0x2000
	s_nop 0
	global_load_lds_dwordx4 v216, s[42:43]
	s_mov_b32 m0, s71
	s_nop 0
	global_load_lds_dwordx4 v210, s[78:79]
	s_mov_b32 m0, s20
	s_nop 0
	global_load_lds_dwordx4 v214, s[78:79]
	s_waitcnt vmcnt(8)
	s_waitcnt lgkmcnt(0)
	s_barrier
	s_setprio 1
	s_waitcnt lgkmcnt(0)
	v_mfma_f32_16x16x32_bf16 v[62:65], v[130:133], v[162:165], v[62:65]
	v_mfma_f32_16x16x32_bf16 v[58:61], v[138:141], v[162:165], v[58:61]
	v_mfma_f32_16x16x32_bf16 v[46:49], v[130:133], v[170:173], v[46:49]
	v_mfma_f32_16x16x32_bf16 v[42:45], v[138:141], v[170:173], v[42:45]
	v_mfma_f32_16x16x32_bf16 v[30:33], v[130:133], v[178:181], v[30:33]
	v_mfma_f32_16x16x32_bf16 v[26:29], v[138:141], v[178:181], v[26:29]
	v_mfma_f32_16x16x32_bf16 v[14:17], v[130:133], v[186:189], v[14:17]
	v_mfma_f32_16x16x32_bf16 v[10:13], v[138:141], v[186:189], v[10:13]
	v_mfma_f32_16x16x32_bf16 v[62:65], v[134:137], v[166:169], v[62:65]
	v_mfma_f32_16x16x32_bf16 v[58:61], v[142:145], v[166:169], v[58:61]
	v_mfma_f32_16x16x32_bf16 v[46:49], v[134:137], v[174:177], v[46:49]
	v_mfma_f32_16x16x32_bf16 v[42:45], v[142:145], v[174:177], v[42:45]
	v_mfma_f32_16x16x32_bf16 v[30:33], v[134:137], v[182:185], v[30:33]
	v_mfma_f32_16x16x32_bf16 v[26:29], v[142:145], v[182:185], v[26:29]
	v_mfma_f32_16x16x32_bf16 v[14:17], v[134:137], v[190:193], v[14:17]
	v_mfma_f32_16x16x32_bf16 v[10:13], v[142:145], v[190:193], v[10:13]
	s_setprio 0
	s_setprio 1
	v_mfma_f32_16x16x32_bf16 v[54:57], v[146:149], v[162:165], v[54:57]
	v_mfma_f32_16x16x32_bf16 v[50:53], v[154:157], v[162:165], v[50:53]
	v_mfma_f32_16x16x32_bf16 v[38:41], v[146:149], v[170:173], v[38:41]
	v_mfma_f32_16x16x32_bf16 v[34:37], v[154:157], v[170:173], v[34:37]
	v_mfma_f32_16x16x32_bf16 v[22:25], v[146:149], v[178:181], v[22:25]
	v_mfma_f32_16x16x32_bf16 v[18:21], v[154:157], v[178:181], v[18:21]
	v_mfma_f32_16x16x32_bf16 v[6:9], v[146:149], v[186:189], v[6:9]
	v_mfma_f32_16x16x32_bf16 v[2:5], v[154:157], v[186:189], v[2:5]
	v_mfma_f32_16x16x32_bf16 v[54:57], v[150:153], v[166:169], v[54:57]
	v_mfma_f32_16x16x32_bf16 v[50:53], v[158:161], v[166:169], v[50:53]
	v_mfma_f32_16x16x32_bf16 v[38:41], v[150:153], v[174:177], v[38:41]
	v_mfma_f32_16x16x32_bf16 v[34:37], v[158:161], v[174:177], v[34:37]
	v_mfma_f32_16x16x32_bf16 v[22:25], v[150:153], v[182:185], v[22:25]
	v_mfma_f32_16x16x32_bf16 v[18:21], v[158:161], v[182:185], v[18:21]
	v_mfma_f32_16x16x32_bf16 v[6:9], v[150:153], v[190:193], v[6:9]
	v_mfma_f32_16x16x32_bf16 v[2:5], v[158:161], v[190:193], v[2:5]
	s_setprio 0
	s_barrier
	s_add_i32 s41, 0, 0x18000
	s_add_i32 s44, 0, 0x1c000
	v_add_u32_e32 v142, s41, v223
	v_add_u32_e32 v158, s44, v223
	ds_read_b128 v[130:133], v142
	ds_read_b128 v[134:137], v142 offset:1024
	ds_read_b128 v[138:141], v142 offset:2048
	ds_read_b128 v[142:145], v142 offset:3072
	ds_read_b128 v[146:149], v158
	ds_read_b128 v[150:153], v158 offset:1024
	ds_read_b128 v[154:157], v158 offset:2048
	ds_read_b128 v[158:161], v158 offset:3072
	s_add_u32 s42, s78, 0x40000
	s_addc_u32 s43, s79, 0
	s_mov_b32 m0, s21
	ds_read_b128 v[162:165], v247 offset:32768
	ds_read_b128 v[166:169], v247 offset:33792
	ds_read_b128 v[170:173], v247 offset:34816
	ds_read_b128 v[174:177], v247 offset:35840
	ds_read_b128 v[178:181], v247 offset:36864
	ds_read_b128 v[182:185], v247 offset:37888
	ds_read_b128 v[186:189], v247 offset:38912
	ds_read_b128 v[190:193], v247 offset:39936
	global_load_lds_dwordx4 v210, s[42:43]
	s_mov_b32 m0, s22
	s_nop 0
	global_load_lds_dwordx4 v214, s[42:43]
	s_waitcnt vmcnt(8)
	s_waitcnt lgkmcnt(0)
	s_barrier
	s_setprio 1
	s_waitcnt lgkmcnt(0)
	v_mfma_f32_16x16x32_bf16 v[126:129], v[130:133], v[162:165], v[126:129]
	v_mfma_f32_16x16x32_bf16 v[122:125], v[138:141], v[162:165], v[122:125]
	v_mfma_f32_16x16x32_bf16 v[110:113], v[130:133], v[170:173], v[110:113]
	v_mfma_f32_16x16x32_bf16 v[106:109], v[138:141], v[170:173], v[106:109]
	v_mfma_f32_16x16x32_bf16 v[94:97], v[130:133], v[178:181], v[94:97]
	v_mfma_f32_16x16x32_bf16 v[90:93], v[138:141], v[178:181], v[90:93]
	v_mfma_f32_16x16x32_bf16 v[78:81], v[130:133], v[186:189], v[78:81]
	v_mfma_f32_16x16x32_bf16 v[74:77], v[138:141], v[186:189], v[74:77]
	v_mfma_f32_16x16x32_bf16 v[126:129], v[134:137], v[166:169], v[126:129]
	v_mfma_f32_16x16x32_bf16 v[122:125], v[142:145], v[166:169], v[122:125]
	v_mfma_f32_16x16x32_bf16 v[110:113], v[134:137], v[174:177], v[110:113]
	v_mfma_f32_16x16x32_bf16 v[106:109], v[142:145], v[174:177], v[106:109]
	v_mfma_f32_16x16x32_bf16 v[94:97], v[134:137], v[182:185], v[94:97]
	v_mfma_f32_16x16x32_bf16 v[90:93], v[142:145], v[182:185], v[90:93]
	v_mfma_f32_16x16x32_bf16 v[78:81], v[134:137], v[190:193], v[78:81]
	v_mfma_f32_16x16x32_bf16 v[74:77], v[142:145], v[190:193], v[74:77]
	s_setprio 0
	s_setprio 1
	v_mfma_f32_16x16x32_bf16 v[118:121], v[146:149], v[162:165], v[118:121]
	v_mfma_f32_16x16x32_bf16 v[114:117], v[154:157], v[162:165], v[114:117]
	v_mfma_f32_16x16x32_bf16 v[102:105], v[146:149], v[170:173], v[102:105]
	v_mfma_f32_16x16x32_bf16 v[98:101], v[154:157], v[170:173], v[98:101]
	v_mfma_f32_16x16x32_bf16 v[86:89], v[146:149], v[178:181], v[86:89]
	v_mfma_f32_16x16x32_bf16 v[82:85], v[154:157], v[178:181], v[82:85]
	v_mfma_f32_16x16x32_bf16 v[70:73], v[146:149], v[186:189], v[70:73]
	v_mfma_f32_16x16x32_bf16 v[66:69], v[154:157], v[186:189], v[66:69]
	v_mfma_f32_16x16x32_bf16 v[118:121], v[150:153], v[166:169], v[118:121]
	v_mfma_f32_16x16x32_bf16 v[114:117], v[158:161], v[166:169], v[114:117]
	v_mfma_f32_16x16x32_bf16 v[102:105], v[150:153], v[174:177], v[102:105]
	v_mfma_f32_16x16x32_bf16 v[98:101], v[158:161], v[174:177], v[98:101]
	v_mfma_f32_16x16x32_bf16 v[86:89], v[150:153], v[182:185], v[86:89]
	v_mfma_f32_16x16x32_bf16 v[82:85], v[158:161], v[182:185], v[82:85]
	v_mfma_f32_16x16x32_bf16 v[70:73], v[150:153], v[190:193], v[70:73]
	v_mfma_f32_16x16x32_bf16 v[66:69], v[158:161], v[190:193], v[66:69]
	s_setprio 0
	s_barrier
	s_add_i32 s41, s41, s39
	s_add_i32 m0, s41, 0xffffff80
	ds_read_b128 v[162:165], v247 offset:49152
	ds_read_b128 v[166:169], v247 offset:50176
	ds_read_b128 v[170:173], v247 offset:51200
	ds_read_b128 v[174:177], v247 offset:52224
	ds_read_b128 v[178:181], v247 offset:53248
	ds_read_b128 v[182:185], v247 offset:54272
	ds_read_b128 v[186:189], v247 offset:55296
	ds_read_b128 v[190:193], v247 offset:56320
	global_load_lds_dwordx4 v212, s[16:17] offset:128
	s_add_i32 m0, s41, 0x1f80
	s_add_i32 s41, s44, s39
	global_load_lds_dwordx4 v216, s[16:17] offset:128
	s_add_u32 s16, s16, 0x40080
	s_addc_u32 s17, s17, 0
	s_mov_b32 m0, s41
	s_nop 0
	global_load_lds_dwordx4 v212, s[16:17]
	s_add_i32 m0, s41, 0x2000
	s_nop 0
	global_load_lds_dwordx4 v216, s[16:17]
	s_add_i32 m0, s14, 0xffffff80
	s_nop 0
	global_load_lds_dwordx4 v210, s[78:79] offset:128
	s_add_i32 m0, s15, 0xffffff80
	s_nop 0
	global_load_lds_dwordx4 v214, s[78:79] offset:128
	s_waitcnt vmcnt(8)
	s_waitcnt lgkmcnt(0)
	s_barrier
	s_setprio 1
	s_waitcnt lgkmcnt(0)
	v_mfma_f32_16x16x32_bf16 v[62:65], v[130:133], v[162:165], v[62:65]
	v_mfma_f32_16x16x32_bf16 v[58:61], v[138:141], v[162:165], v[58:61]
	v_mfma_f32_16x16x32_bf16 v[46:49], v[130:133], v[170:173], v[46:49]
	v_mfma_f32_16x16x32_bf16 v[42:45], v[138:141], v[170:173], v[42:45]
	v_mfma_f32_16x16x32_bf16 v[30:33], v[130:133], v[178:181], v[30:33]
	v_mfma_f32_16x16x32_bf16 v[26:29], v[138:141], v[178:181], v[26:29]
	v_mfma_f32_16x16x32_bf16 v[14:17], v[130:133], v[186:189], v[14:17]
	v_mfma_f32_16x16x32_bf16 v[10:13], v[138:141], v[186:189], v[10:13]
	v_mfma_f32_16x16x32_bf16 v[62:65], v[134:137], v[166:169], v[62:65]
	v_mfma_f32_16x16x32_bf16 v[58:61], v[142:145], v[166:169], v[58:61]
	v_mfma_f32_16x16x32_bf16 v[46:49], v[134:137], v[174:177], v[46:49]
	v_mfma_f32_16x16x32_bf16 v[42:45], v[142:145], v[174:177], v[42:45]
	v_mfma_f32_16x16x32_bf16 v[30:33], v[134:137], v[182:185], v[30:33]
	v_mfma_f32_16x16x32_bf16 v[26:29], v[142:145], v[182:185], v[26:29]
	v_mfma_f32_16x16x32_bf16 v[14:17], v[134:137], v[190:193], v[14:17]
	v_mfma_f32_16x16x32_bf16 v[10:13], v[142:145], v[190:193], v[10:13]
	s_setprio 0
	s_setprio 1
	v_mfma_f32_16x16x32_bf16 v[54:57], v[146:149], v[162:165], v[54:57]
	v_mfma_f32_16x16x32_bf16 v[50:53], v[154:157], v[162:165], v[50:53]
	v_mfma_f32_16x16x32_bf16 v[38:41], v[146:149], v[170:173], v[38:41]
	v_mfma_f32_16x16x32_bf16 v[34:37], v[154:157], v[170:173], v[34:37]
	v_mfma_f32_16x16x32_bf16 v[22:25], v[146:149], v[178:181], v[22:25]
	v_mfma_f32_16x16x32_bf16 v[18:21], v[154:157], v[178:181], v[18:21]
	v_mfma_f32_16x16x32_bf16 v[6:9], v[146:149], v[186:189], v[6:9]
	v_mfma_f32_16x16x32_bf16 v[2:5], v[154:157], v[186:189], v[2:5]
	v_mfma_f32_16x16x32_bf16 v[54:57], v[150:153], v[166:169], v[54:57]
	v_mfma_f32_16x16x32_bf16 v[50:53], v[158:161], v[166:169], v[50:53]
	v_mfma_f32_16x16x32_bf16 v[38:41], v[150:153], v[174:177], v[38:41]
	v_mfma_f32_16x16x32_bf16 v[34:37], v[158:161], v[174:177], v[34:37]
	v_mfma_f32_16x16x32_bf16 v[22:25], v[150:153], v[182:185], v[22:25]
	v_mfma_f32_16x16x32_bf16 v[18:21], v[158:161], v[182:185], v[18:21]
	v_mfma_f32_16x16x32_bf16 v[6:9], v[150:153], v[190:193], v[6:9]
	v_mfma_f32_16x16x32_bf16 v[2:5], v[158:161], v[190:193], v[2:5]
	s_setprio 0
	s_barrier
	s_add_i32 s40, s40, 2
	s_add_u32 s6, s6, 0x100
	s_addc_u32 s7, s7, 0
	s_add_u32 s35, s35, 0x100
	s_addc_u32 s37, s37, 0
	s_cmp_gt_u32 s40, 13
	s_cbranch_scc0 .LBB0_120
	s_and_b64 vcc, exec, s[48:49]
	s_cbranch_vccz .LBB0_123
	s_barrier
